# ph0: layer-0 weight conversion in two stages (bulk on WGs 176-255, remainder over all WGs) so all WGs finish together; tables on WGs 168-175
# baseline (speedup 1.0000x reference)
.LBB0_8:
	s_or_b64 exec, exec, s[2:3]
	s_waitcnt lgkmcnt(0)
	s_barrier
	s_load_dwordx2 s[44:45], s[0:1], 0xd8
	s_waitcnt lgkmcnt(0)
	s_cmp_ge_i32 s44, s45
	s_cbranch_scc1 .LBB0_864
	s_load_dword s2, s[0:1], 0xe0
	s_lshl_b32 s64, s33, 3
	s_load_dwordx2 s[0:1], s[0:1], 0xc8
	s_lshl_b32 s28, s33, 9
	v_lshrrev_b32_e32 v2, 20, v0
	s_waitcnt lgkmcnt(0)
	s_cmp_lg_u32 s2, 0
	s_cselect_b64 s[30:31], -1, 0
	v_writelane_b32 v253, s0, 5
	s_add_i32 s26, s44, 1
	v_lshrrev_b32_e32 v0, 10, v0
	v_writelane_b32 v253, s1, 6
	s_and_b32 s0, s33, 7
	s_cmp_eq_u32 s0, 0
	s_cselect_b64 s[0:1], -1, 0
	v_writelane_b32 v253, s0, 7
	s_ashr_i32 s53, s33, 31
	v_or_b32_e32 v0, v0, v2
	v_writelane_b32 v253, s1, 8
	s_lshr_b32 s0, s53, 29
	s_add_i32 s0, s33, s0
	s_ashr_i32 s0, s0, 3
	s_cmpk_lg_i32 s33, 0x100
	v_writelane_b32 v253, s0, 9
	s_cselect_b64 s[0:1], -1, 0
	v_writelane_b32 v253, s0, 10
	v_mov_b32_e32 v145, 0
	v_mov_b32_e32 v247, 0x358637bd
	v_writelane_b32 v253, s1, 11
	s_add_u32 s0, s78, 0xdc00000
	s_addc_u32 s1, s79, 0
	v_writelane_b32 v253, s0, 12
	v_mov_b32_e32 v236, 0x2000
	v_mov_b32_e32 v237, 1
	v_writelane_b32 v253, s1, 13
	s_add_u32 s0, s78, 0xdd00000
	s_addc_u32 s1, s79, 0
	v_writelane_b32 v253, s0, 14
	v_mov_b32_e32 v239, 0x9000
	v_mov_b32_e32 v245, 0x3e000000
	v_writelane_b32 v253, s1, 15
	s_add_u32 s0, s78, 0xde00000
	s_addc_u32 s1, s79, 0
	v_writelane_b32 v253, s0, 16
	s_movk_i32 s65, 0x88
	s_mov_b32 s95, 0x20000
	v_writelane_b32 v253, s1, 17
	s_add_u32 s0, s78, 0xda00000
	s_addc_u32 s1, s79, 0
	s_cmp_gt_i32 s33, 64
	v_writelane_b32 v253, s0, 18
	s_cselect_b32 s3, 64, 0
	s_ashr_i32 s29, s28, 31
	v_writelane_b32 v253, s1, 19
	s_sub_i32 s0, s33, s3
	s_lshl_b32 s1, s0, 3
	s_lshl_b32 s0, s0, 9
	v_writelane_b32 v253, s1, 20
	s_cmp_lt_i32 s2, 0
	v_writelane_b32 v253, s0, 21
	s_cselect_b64 s[0:1], -1, 0
	v_writelane_b32 v253, s0, 22
	s_mov_b32 s54, 0x9000
	s_movk_i32 s66, 0x1000
	v_writelane_b32 v253, s1, 23
	s_add_u32 s0, s78, 0x26400000
	v_writelane_b32 v253, s0, 24
	s_addc_u32 s0, s79, 0
	s_add_u32 s34, s78, 0x26400200
	s_addc_u32 s35, s79, 0
	s_add_u32 s36, s78, 0x26400400
	s_addc_u32 s37, s79, 0
	s_add_u32 s24, s78, 0x26400500
	s_addc_u32 s25, s79, 0
	s_add_u32 s16, s78, 0x26400600
	s_addc_u32 s17, s79, 0
	s_add_u32 s18, s78, 0x26400700
	s_addc_u32 s19, s79, 0
	s_add_u32 s20, s78, 0x26400800
	s_addc_u32 s21, s79, 0
	s_add_u32 s22, s78, 0x26400900
	s_addc_u32 s23, s79, 0
	s_add_u32 s42, s78, 0x26400a00
	s_addc_u32 s43, s79, 0
	s_add_u32 s46, s78, 0x26400b00
	s_addc_u32 s47, s79, 0
	s_add_u32 s48, s78, 0x26400c00
	s_addc_u32 s49, s79, 0
	s_add_u32 s60, s78, 0x26400d00
	s_addc_u32 s61, s79, 0
	s_add_u32 s62, s78, 0x26400e00
	s_addc_u32 s63, s79, 0
	s_add_u32 s72, s78, 0x26400f00
	s_addc_u32 s73, s79, 0
	s_add_u32 s82, s78, 0x26401000
	s_addc_u32 s83, s79, 0
	s_add_u32 s84, s78, 0x26401100
	s_addc_u32 s85, s79, 0
	s_add_u32 s86, s78, 0x26401200
	s_addc_u32 s87, s79, 0
	s_add_u32 s88, s78, 0x26401300
	s_addc_u32 s89, s79, 0
	v_writelane_b32 v253, s0, 25
	s_add_u32 s0, s78, 0x26403400
	s_addc_u32 s1, s79, 0
	v_writelane_b32 v253, s0, 26
	s_movk_i32 s69, 0x300
	s_movk_i32 s68, 0x2000
	v_writelane_b32 v253, s1, 27
	s_add_u32 s0, s78, 0x26403500
	s_addc_u32 s1, s79, 0
	s_abs_i32 s2, s33
	v_cvt_f32_u32_e32 v1, s2
	v_writelane_b32 v253, s0, 28
	s_mov_b32 s59, 0x12000
	s_mov_b32 s67, 0x24000
	v_rcp_iflag_f32_e32 v1, v1
	v_writelane_b32 v253, s1, 29
	s_movk_i32 s0, 0x3ff
	v_and_or_b32 v0, v0, s0, v244
	v_mul_f32_e32 v1, 0x4f7ffffe, v1
	v_cvt_u32_f32_e32 v1, v1
	s_sub_i32 s0, 0, s2
	s_mov_b32 s81, 0x2081cea
	s_mov_b32 s74, 0x36000
	v_readfirstlane_b32 s1, v1
	s_mul_i32 s0, s0, s1
	s_mul_hi_u32 s0, s1, s0
	s_add_i32 s0, s1, s0
	v_writelane_b32 v253, s0, 30
	s_mul_hi_u32 s0, s0, 0x5c0
	s_mul_i32 s0, s0, s2
	s_sub_i32 s0, 0x5c0, s0
	s_sub_i32 s1, s0, s2
	s_cmp_ge_u32 s0, s2
	s_cselect_b32 s0, s1, s0
	s_sub_i32 s1, s0, s2
	s_cmp_ge_u32 s0, s2
	v_writelane_b32 v253, s2, 31
	s_cselect_b32 s0, s1, s0
	v_writelane_b32 v253, s0, 32
	s_lshl_b32 s0, s33, 12
	s_lshl_b32 s1, s3, 12
	v_writelane_b32 v253, s3, 33
	s_sub_i32 s0, s0, s1
	v_writelane_b32 v253, s0, 34
	s_mul_i32 s0, s33, 0x11000
	s_mul_hi_i32 s1, s28, 0x88
	v_writelane_b32 v253, s0, 35
	s_movk_i32 s2, 0x3000
	s_mov_b32 s3, 0x22000000
	v_writelane_b32 v253, s1, 36
	s_lshl_b32 s0, s33, 4
	v_writelane_b32 v253, s0, 37
	s_lshl_b32 s0, s33, 10
	v_writelane_b32 v253, s0, 38
	s_lshl_b32 s0, s33, 11
	v_writelane_b32 v253, s0, 39
	s_add_i32 s0, 0, 0x2020c
	v_writelane_b32 v253, s0, 40
	s_add_i32 s0, 0, 0x20208
	v_writelane_b32 v253, s0, 41
	s_add_i32 s0, 0, 0x20210
	v_writelane_b32 v253, s0, 42
	s_add_i32 s0, 0, 0x20000
	v_writelane_b32 v253, s0, 43
	s_add_i32 s0, 0, 0x20020
	v_writelane_b32 v253, s0, 44
	s_add_i32 s0, 0, 0x20080
	v_writelane_b32 v253, s0, 45
	s_add_i32 s0, 0, 0x20090
	v_writelane_b32 v253, s0, 46
	s_add_i32 s0, 0, 0x20048
	v_writelane_b32 v253, s0, 47
	s_add_i32 s0, 0, 0x20028
	v_writelane_b32 v253, s0, 48
	s_add_i32 s0, 0, 0x20008
	v_writelane_b32 v253, s0, 49
	s_add_i32 s0, 0, 0x20010
	v_writelane_b32 v253, s0, 50
	s_add_i32 s0, 0, 0x20018
	v_writelane_b32 v253, s0, 51
	s_add_i32 s0, 0, 0x20058
	v_writelane_b32 v253, s0, 52
	s_add_i32 s0, 0, 0x20068
	v_writelane_b32 v253, s0, 53
	s_add_i32 s0, 0, 0x20078
	v_writelane_b32 v253, s0, 54
	s_add_i32 s0, 0, 0x200a0
	v_writelane_b32 v253, s0, 55
	s_add_i32 s0, 0, 0x200b0
	v_writelane_b32 v253, s0, 56
	s_add_i32 s0, 0, 0x200c0
	v_writelane_b32 v253, s0, 57
	s_add_i32 s0, 0, 0x20098
	v_writelane_b32 v253, s0, 58
	s_add_i32 s0, 0, 0x20040
	v_writelane_b32 v253, s0, 59
	s_add_i32 s0, 0, 0x20038
	v_writelane_b32 v253, s0, 60
	s_add_i32 s0, 0, 0x20030
	v_writelane_b32 v253, s0, 61
	s_add_i32 s0, 0, 0x20200
	v_writelane_b32 v253, s0, 62
	s_add_i32 s0, 0, 0x20204
	v_writelane_b32 v253, s0, 63
	s_mov_b32 s75, 0x3f000
	v_readlane_b32 s0, v253, 0
	s_mov_b32 s52, s0
	s_mov_b32 s27, 0
	v_cmp_eq_u32_e64 s[0:1], 0, v0
	s_mov_b64 s[70:71], 0x200
	s_mov_b64 s[50:51], 0x80
	v_writelane_b32 v254, s0, 0
	s_nop 1
	v_writelane_b32 v254, s1, 1
	s_lshl_b64 s[0:1], s[28:29], 7
	v_writelane_b32 v254, s0, 2
	s_nop 1
	v_writelane_b32 v254, s1, 3
	s_lshl_b64 s[0:1], s[28:29], 6
	v_writelane_b32 v254, s0, 4
	s_nop 1
	v_writelane_b32 v254, s1, 5
	s_lshl_b64 s[0:1], s[28:29], 2
	v_writelane_b32 v254, s0, 6
	s_nop 1
	v_writelane_b32 v254, s1, 7
	s_lshl_b64 s[0:1], s[28:29], 1
	v_writelane_b32 v254, s0, 8
	s_nop 1
	v_writelane_b32 v254, s1, 9
	v_writelane_b32 v254, s28, 10
	s_nop 1
	v_writelane_b32 v254, s29, 11
	v_writelane_b32 v254, s30, 12
	s_nop 1
	v_writelane_b32 v254, s31, 13
	v_writelane_b32 v254, s34, 14
	s_nop 1
	v_writelane_b32 v254, s35, 15
	v_writelane_b32 v254, s36, 16
	s_nop 1
	v_writelane_b32 v254, s37, 17
	v_writelane_b32 v254, s24, 18
	s_nop 1
	v_writelane_b32 v254, s25, 19
	v_writelane_b32 v254, s16, 20
	s_nop 1
	v_writelane_b32 v254, s17, 21
	v_writelane_b32 v254, s18, 22
	s_nop 1
	v_writelane_b32 v254, s19, 23
	v_writelane_b32 v254, s20, 24
	s_nop 1
	v_writelane_b32 v254, s21, 25
	v_writelane_b32 v254, s22, 26
	s_nop 1
	v_writelane_b32 v254, s23, 27
	v_writelane_b32 v254, s64, 28
	v_writelane_b32 v254, s26, 29
	v_writelane_b32 v254, s42, 30
	s_nop 1
	v_writelane_b32 v254, s43, 31
	v_writelane_b32 v254, s46, 32
	s_nop 1
	v_writelane_b32 v254, s47, 33
	v_writelane_b32 v254, s48, 34
	s_nop 1
	v_writelane_b32 v254, s49, 35
	v_writelane_b32 v254, s60, 36
	s_nop 1
	v_writelane_b32 v254, s61, 37
	v_writelane_b32 v254, s62, 38
	s_nop 1
	v_writelane_b32 v254, s63, 39
	v_writelane_b32 v254, s72, 40
	s_nop 1
	v_writelane_b32 v254, s73, 41
	v_writelane_b32 v254, s82, 42
	s_nop 1
	v_writelane_b32 v254, s83, 43
	v_writelane_b32 v254, s84, 44
	s_nop 1
	v_writelane_b32 v254, s85, 45
	v_writelane_b32 v254, s86, 46
	s_nop 1
	v_writelane_b32 v254, s87, 47
	v_writelane_b32 v254, s88, 48
	s_nop 1
	v_writelane_b32 v254, s89, 49
	s_mov_b32 s99, 0
	s_mov_b32 s101, 0
	s_branch .LBB0_13

.LBB0_689:
	s_add_i32 s0, s52, 0xffffff58
	s_cmpk_eq_i32 s33, 0x100
	s_cselect_b32 s0, s0, s52
	v_lshl_add_u32 v12, s0, 9, v84
	v_cmp_gt_u32_e32 vcc, s66, v12
	s_and_saveexec_b64 s[4:5], vcc
	s_cbranch_execz .LBB0_692
	v_readlane_b32 s0, v253, 52
	v_ashrrev_i32_e32 v13, 31, v12
	v_lshlrev_b64 v[18:19], 6, v[12:13]
	v_mov_b32_e32 v0, s0
	v_readlane_b32 s0, v253, 53
	v_lshlrev_b64 v[16:17], 7, v[12:13]
	v_or_b32_e32 v18, 60, v18
	v_mov_b32_e32 v4, s0
	v_readlane_b32 s0, v253, 54
	ds_read2_b64 v[0:3], v0 offset1:1
	ds_read2_b64 v[4:7], v4 offset1:1
	v_mov_b32_e32 v8, s0
	ds_read_b64 v[14:15], v8
	v_lshlrev_b64 v[20:21], 2, v[12:13]
	v_mad_i64_i32 v[22:23], s[0:1], v12, s65, 0
	s_mov_b64 s[6:7], 0

.LBB0_697:
	s_mov_b32 s98, 0xc400
	s_cmpk_lg_i32 s33, 0x100
	s_cbranch_scc1 .Ltr_entry
	s_mov_b32 s100, s17
	s_add_i32 s17, s17, 0xfffffa80
	s_cmp_lt_i32 s17, 0
	s_cbranch_scc1 .Ltr_stage_b
	s_movk_i32 s98, 0x3100
	s_movk_i32 s64, 0x280
	s_addk_i32 s17, 0x1000
	s_mov_b32 s101, 1
	s_branch .Ltr_entry
.Ltr_stage_b:
	s_mov_b32 s101, 0
	s_mov_b32 s17, s100
	s_movk_i32 s98, 0x1000
	v_readlane_b32 s64, v254, 28
	v_readfirstlane_b32 s16, v84
	s_ashr_i32 s16, s16, 6

.LBB0_743:
	s_cmp_eq_u32 s101, 1
	s_cbranch_scc1 .Ltr_stage_b
	v_readlane_b32 s64, v254, 28
	v_readlane_b32 s28, v254, 10
	v_readlane_b32 s30, v254, 12
	v_readlane_b32 s34, v254, 14
	v_readlane_b32 s36, v254, 16
	v_readlane_b32 s24, v254, 18
	v_readlane_b32 s16, v254, 20
	v_readlane_b32 s18, v254, 22
	v_readlane_b32 s20, v254, 24
	v_readlane_b32 s22, v254, 26
	s_mov_b64 s[0:1], 0
	v_readlane_b32 s29, v254, 11
	v_readlane_b32 s31, v254, 13
	v_readlane_b32 s26, v254, 29
	v_readlane_b32 s35, v254, 15
	v_readlane_b32 s37, v254, 17
	v_readlane_b32 s25, v254, 19
	v_readlane_b32 s17, v254, 21
	v_readlane_b32 s19, v254, 23
	v_readlane_b32 s21, v254, 25
	v_readlane_b32 s23, v254, 27
	s_mov_b64 s[38:39], s[40:41]
